# attention QK and PV: K/V fragment LDS reads triple-buffered with counted lgkmcnt instead of read-wait-mfma serialization
# speedup vs baseline: 1.0655x; 1.0062x over previous
; #define MFMA(a, b, c) __builtin_amdgcn_mfma_f32_32x32x16_bf16((a), (b), (c), 0, 0, 0)
; DI void attn_item(const Params& p, int l, int b, int head, int qt, float lam, float lam_init, unsigned char* smem) {
;     ...
; #pragma unroll
;       for (int ks = 0; ks < 4; ++ks) {
; #pragma unroll
;         for (int sub = 0; sub < 2; ++sub) {
;           const bf16x8 kf = *(const bf16x8*)(Kt + (sub * 32 + r) * 272 + (comp * 64 + ks * 16 + h * 8) * 2);
;           s[sub] = MFMA(kf, qf[ks], s[sub]);
;         }
;       }
;       float mx = -INFINITY;
;       if (!past) {
;         const float qk0 = (float)(qpos - kt * 64 - 4 * h);
;         const float qb = slope2 * (float)qpos;
; #pragma unroll
;         for (int sub = 0; sub < 2; ++sub)
; #pragma unroll
;           for (int i = 0; i < 16; ++i) {
;             const float d = qk0 - (float)(sub * 32 + (i & 3) + 8 * (i >> 2));
;             s[sub][i] = s[sub][i] - slope2 * fabsf(d) + qb;
;           }
;       }
.LBB0_478:
	s_or_b64 exec, exec, s[8:9]
	s_bitcmp1_b32 s48, 0
	s_cselect_b32 s0, 0x8800, 0
	s_add_i32 s8, s0, 0
	v_add_u32_e32 v190, s8, v178
	v_add3_u32 v190, v190, v130, v187
	ds_read_b128 v[192:195], v190 offset:64
	ds_read_b128 v[196:199], v190 offset:8768
	ds_read_b128 v[248:251], v190 offset:96
	s_waitcnt lgkmcnt(2)
	v_mfma_f32_32x32x16_bf16 v[80:95], v[192:195], v[108:111], v[80:95]
	ds_read_b128 v[192:195], v190 offset:8800
	s_waitcnt lgkmcnt(2)
	v_mfma_f32_32x32x16_bf16 v[64:79], v[196:199], v[108:111], v[64:79]
	ds_read_b128 v[196:199], v190 offset:128
	s_waitcnt lgkmcnt(2)
	v_mfma_f32_32x32x16_bf16 v[80:95], v[248:251], v[112:115], v[80:95]
	ds_read_b128 v[248:251], v190 offset:8832
	s_waitcnt lgkmcnt(2)
	v_mfma_f32_32x32x16_bf16 v[64:79], v[192:195], v[112:115], v[64:79]
	ds_read_b128 v[192:195], v190 offset:160
	s_waitcnt lgkmcnt(2)
	v_mfma_f32_32x32x16_bf16 v[80:95], v[196:199], v[116:119], v[80:95]
	ds_read_b128 v[196:199], v190 offset:8864
	s_waitcnt lgkmcnt(2)
	v_mfma_f32_32x32x16_bf16 v[64:79], v[248:251], v[116:119], v[64:79]
	s_waitcnt lgkmcnt(1)
	v_mfma_f32_32x32x16_bf16 v[80:95], v[192:195], v[124:127], v[80:95]
	s_waitcnt lgkmcnt(0)
	v_mfma_f32_32x32x16_bf16 v[64:79], v[196:199], v[124:127], v[64:79]
	s_and_saveexec_b64 s[0:1], vcc
	s_cbranch_execz .LBB0_480
	v_cvt_f32_i32_e32 v190, v189
	s_mov_b32 s48, -2.0
	s_mov_b32 s49, 0xc0400000
	v_pk_add_f32 v[192:193], v[190:191], s[48:49] op_sel_hi:[0,1]
	s_mov_b32 s48, 0xc1000000
	s_mov_b32 s49, 0xc1100000
	v_pk_add_f32 v[194:195], v[190:191], s[48:49] op_sel_hi:[0,1]
	s_mov_b32 s48, 0xc1200000
	s_mov_b32 s49, 0xc1300000
	v_pk_add_f32 v[196:197], v[190:191], s[48:49] op_sel_hi:[0,1]
	s_mov_b32 s48, 0xc1800000
	s_mov_b32 s49, 0xc1880000
	v_pk_add_f32 v[198:199], v[190:191], s[48:49] op_sel_hi:[0,1]
	s_mov_b32 s48, 0xc1900000
	s_mov_b32 s49, 0xc1980000
	v_pk_add_f32 v[200:201], v[190:191], s[48:49] op_sel_hi:[0,1]
	s_mov_b32 s48, 0xc1c00000
	s_mov_b32 s49, 0xc1c80000
	v_pk_add_f32 v[202:203], v[190:191], s[48:49] op_sel_hi:[0,1]
	s_mov_b32 s48, 0xc1d00000
	s_mov_b32 s49, 0xc1d80000
	v_pk_add_f32 v[204:205], v[190:191], s[48:49] op_sel_hi:[0,1]
	s_mov_b32 s48, 0xc2000000
	s_mov_b32 s49, 0xc2040000
	v_pk_add_f32 v[206:207], v[190:191], s[48:49] op_sel_hi:[0,1]
	s_mov_b32 s48, 0xc2080000
	s_mov_b32 s49, 0xc20c0000
	v_pk_add_f32 v[208:209], v[190:191], s[48:49] op_sel_hi:[0,1]
	s_mov_b32 s48, 0xc2200000
	s_mov_b32 s49, 0xc2240000
	v_pk_add_f32 v[210:211], v[190:191], s[48:49] op_sel_hi:[0,1]
	s_mov_b32 s48, 0xc2280000
	s_mov_b32 s49, 0xc22c0000
	v_pk_add_f32 v[234:235], v[190:191], s[48:49] op_sel_hi:[0,1]
	s_mov_b32 s48, 0xc2400000
	s_mov_b32 s49, 0xc2440000
	v_pk_add_f32 v[236:237], v[190:191], s[48:49] op_sel_hi:[0,1]
	s_mov_b32 s48, 0xc2480000
	s_mov_b32 s49, 0xc24c0000
	v_pk_add_f32 v[238:239], v[190:191], s[48:49] op_sel_hi:[0,1]
	s_mov_b32 s48, 0xc2600000
	s_mov_b32 s49, 0xc2640000
	v_pk_add_f32 v[240:241], v[190:191], s[48:49] op_sel_hi:[0,1]
	s_mov_b32 s48, 0xc2680000
	s_mov_b32 s49, 0xc26c0000
	v_pk_add_f32 v[242:243], v[190:191], s[48:49] op_sel_hi:[0,1]
	v_and_b32_e32 v193, 0x7fffffff, v193
	v_and_b32_e32 v192, 0x7fffffff, v192
	s_xor_b32 s49, s16, 0x80000000
	s_xor_b32 s48, s15, 0x80000000
	v_and_b32_e32 v195, 0x7fffffff, v195
	v_and_b32_e32 v194, 0x7fffffff, v194
	v_pk_fma_f32 v[82:83], s[48:49], v[192:193], v[82:83]
	s_xor_b32 s49, s18, 0x80000000
	s_xor_b32 s48, s17, 0x80000000
	v_and_b32_e32 v197, 0x7fffffff, v197
	v_and_b32_e32 v196, 0x7fffffff, v196
	v_pk_fma_f32 v[84:85], s[48:49], v[194:195], v[84:85]
	s_xor_b32 s49, s20, 0x80000000
	s_xor_b32 s48, s19, 0x80000000
	v_and_b32_e32 v199, 0x7fffffff, v199
	v_and_b32_e32 v198, 0x7fffffff, v198
	v_pk_fma_f32 v[86:87], s[48:49], v[196:197], v[86:87]
	s_xor_b32 s49, s22, 0x80000000
	s_xor_b32 s48, s21, 0x80000000
	v_and_b32_e32 v201, 0x7fffffff, v201
	v_and_b32_e32 v200, 0x7fffffff, v200
	v_pk_fma_f32 v[88:89], s[48:49], v[198:199], v[88:89]
	s_xor_b32 s49, s24, 0x80000000
	s_xor_b32 s48, s23, 0x80000000
	v_and_b32_e32 v203, 0x7fffffff, v203
	v_and_b32_e32 v202, 0x7fffffff, v202
	v_pk_fma_f32 v[90:91], s[48:49], v[200:201], v[90:91]
	s_xor_b32 s49, s26, 0x80000000
	s_xor_b32 s48, s25, 0x80000000
	v_and_b32_e32 v205, 0x7fffffff, v205
	v_and_b32_e32 v204, 0x7fffffff, v204
	v_pk_fma_f32 v[92:93], s[48:49], v[202:203], v[92:93]
	s_xor_b32 s49, s28, 0x80000000
	s_xor_b32 s48, s27, 0x80000000
	v_and_b32_e32 v207, 0x7fffffff, v207
	v_and_b32_e32 v206, 0x7fffffff, v206
	v_pk_fma_f32 v[94:95], s[48:49], v[204:205], v[94:95]
	s_xor_b32 s49, s30, 0x80000000
	s_xor_b32 s48, s29, 0x80000000
	v_and_b32_e32 v209, 0x7fffffff, v209
	v_and_b32_e32 v208, 0x7fffffff, v208
	v_pk_fma_f32 v[64:65], s[48:49], v[206:207], v[64:65]
	s_xor_b32 s49, s34, 0x80000000
	s_xor_b32 s48, s31, 0x80000000
	v_and_b32_e32 v211, 0x7fffffff, v211
	v_and_b32_e32 v210, 0x7fffffff, v210
	v_pk_fma_f32 v[66:67], s[48:49], v[208:209], v[66:67]
	s_xor_b32 s49, s36, 0x80000000
	s_xor_b32 s48, s35, 0x80000000
	v_and_b32_e32 v235, 0x7fffffff, v235
	v_and_b32_e32 v234, 0x7fffffff, v234
	v_pk_fma_f32 v[68:69], s[48:49], v[210:211], v[68:69]
	s_xor_b32 s49, s38, 0x80000000
	s_xor_b32 s48, s37, 0x80000000
	v_and_b32_e32 v237, 0x7fffffff, v237
	v_and_b32_e32 v236, 0x7fffffff, v236
	v_pk_fma_f32 v[70:71], s[48:49], v[234:235], v[70:71]
	s_xor_b32 s49, s40, 0x80000000
	s_xor_b32 s48, s39, 0x80000000
	v_and_b32_e32 v239, 0x7fffffff, v239
	v_and_b32_e32 v238, 0x7fffffff, v238
	v_pk_fma_f32 v[72:73], s[48:49], v[236:237], v[72:73]
	s_xor_b32 s49, s42, 0x80000000
	s_xor_b32 s48, s41, 0x80000000
	v_add_f32_e32 v245, -1.0, v190
	v_and_b32_e32 v241, 0x7fffffff, v241
	v_and_b32_e32 v240, 0x7fffffff, v240
	v_pk_fma_f32 v[74:75], s[48:49], v[238:239], v[74:75]
	s_xor_b32 s49, s44, 0x80000000
	s_xor_b32 s48, s43, 0x80000000
	v_and_b32_e32 v243, 0x7fffffff, v243
	v_and_b32_e32 v242, 0x7fffffff, v242
	v_and_b32_e32 v244, 0x7fffffff, v190
	v_and_b32_e32 v245, 0x7fffffff, v245
	v_pk_fma_f32 v[76:77], s[48:49], v[240:241], v[76:77]
	s_xor_b32 s49, s46, 0x80000000
	s_xor_b32 s48, s45, 0x80000000
	v_pk_fma_f32 v[78:79], s[48:49], v[242:243], v[78:79]
	v_pk_fma_f32 v[80:81], s[2:3], v[244:245], v[80:81] neg_lo:[1,0,0] neg_hi:[1,0,0]
	v_pk_add_f32 v[78:79], v[172:173], v[78:79]
	v_pk_add_f32 v[76:77], v[170:171], v[76:77]
	v_pk_add_f32 v[74:75], v[168:169], v[74:75]
	v_pk_add_f32 v[72:73], v[166:167], v[72:73]
	v_pk_add_f32 v[70:71], v[164:165], v[70:71]
	v_pk_add_f32 v[68:69], v[162:163], v[68:69]
	v_pk_add_f32 v[66:67], v[160:161], v[66:67]
	v_pk_add_f32 v[64:65], v[158:159], v[64:65]
	v_pk_add_f32 v[94:95], v[156:157], v[94:95]
	v_pk_add_f32 v[92:93], v[154:155], v[92:93]
	v_pk_add_f32 v[90:91], v[152:153], v[90:91]
	v_pk_add_f32 v[88:89], v[150:151], v[88:89]
	v_pk_add_f32 v[86:87], v[148:149], v[86:87]
	v_pk_add_f32 v[84:85], v[146:147], v[84:85]
	v_pk_add_f32 v[82:83], v[144:145], v[82:83]
	v_pk_add_f32 v[80:81], v[142:143], v[80:81]

; #define MFMA(a, b, c) __builtin_amdgcn_mfma_f32_32x32x16_bf16((a), (b), (c), 0, 0, 0)
; DI float fexp2(float x) { return __builtin_amdgcn_exp2f(x); }
; DI void attn_item(const Params& p, int l, int b, int head, int qt, float lam, float lam_init, unsigned char* smem) {
;     ...
;         const float m_new = fmaxf(m_run, mx);
;         const float alpha = fexp2(m_run - m_new);
;         m_run = m_new;
;         float lsum = 0.f;
; #pragma unroll
;         for (int sub = 0; sub < 2; ++sub)
; #pragma unroll
;           for (int i = 0; i < 16; ++i) {
;             const float pv = fexp2(s[sub][i] - m_new);
;             lsum += pv;
;             s[sub][i] = pv;
;           }
;         l_run = l_run * alpha + lsum;
;         if (__ballot(alpha != 1.f) != 0ull) {
; #pragma unroll
;           for (int dt = 0; dt < 4; ++dt)
; #pragma unroll
;             for (int i = 0; i < 16; ++i) O[dt][i] *= alpha;
;         }
; #pragma unroll
;         for (int sub = 0; sub < 2; ++sub)
; #pragma unroll
;           for (int s2 = 0; s2 < 2; ++s2) {
;             const bf16x8 pf = pack8(s[sub], s2);
; #pragma unroll
;             for (int dt = 0; dt < 4; ++dt) {
;               const unsigned char* va = Vt + (dt * 32 + r) * 136 + (sub * 32 + s2 * 16 + 4 * h) * 2;
;               const uint2 lo = *(const uint2*)va;
;               const uint2 hi = *(const uint2*)(va + 16);
;               const uint4 vv = make_uint4(lo.x, lo.y, hi.x, hi.y);
;               O[dt] = MFMA(__builtin_bit_cast(bf16x8, vv), pf, O[dt]);
;             }
;           }
.LBB0_483:
	v_sub_f32_e32 v80, v80, v190
	v_exp_f32_e32 v192, v80
	v_sub_f32_e32 v81, v81, v190
	v_exp_f32_e32 v193, v81
	v_sub_f32_e32 v81, v82, v190
	v_exp_f32_e32 v194, v81
	v_sub_f32_e32 v81, v83, v190
	v_exp_f32_e32 v195, v81
	v_sub_f32_e32 v81, v84, v190
	v_add_f32_e32 v80, 0, v192
	v_exp_f32_e32 v196, v81
	v_sub_f32_e32 v81, v85, v190
	v_add_f32_e32 v80, v193, v80
	v_exp_f32_e32 v197, v81
	v_sub_f32_e32 v81, v86, v190
	v_add_f32_e32 v80, v194, v80
	v_exp_f32_e32 v198, v81
	v_sub_f32_e32 v81, v87, v190
	v_add_f32_e32 v80, v195, v80
	v_exp_f32_e32 v199, v81
	v_sub_f32_e32 v81, v88, v190
	v_add_f32_e32 v80, v196, v80
	v_exp_f32_e32 v88, v81
	v_sub_f32_e32 v81, v89, v190
	v_add_f32_e32 v80, v197, v80
	v_exp_f32_e32 v89, v81
	v_sub_f32_e32 v81, v90, v190
	v_add_f32_e32 v80, v198, v80
	v_exp_f32_e32 v90, v81
	v_sub_f32_e32 v81, v91, v190
	v_add_f32_e32 v80, v199, v80
	v_exp_f32_e32 v91, v81
	v_sub_f32_e32 v81, v92, v190
	v_add_f32_e32 v80, v88, v80
	v_exp_f32_e32 v92, v81
	v_sub_f32_e32 v81, v93, v190
	v_add_f32_e32 v80, v89, v80
	v_exp_f32_e32 v93, v81
	v_sub_f32_e32 v81, v94, v190
	v_add_f32_e32 v80, v90, v80
	v_exp_f32_e32 v94, v81
	v_sub_f32_e32 v81, v95, v190
	v_add_f32_e32 v80, v91, v80
	v_exp_f32_e32 v95, v81
	v_add_f32_e32 v80, v92, v80
	v_add_f32_e32 v80, v93, v80
	v_add_f32_e32 v80, v94, v80
	v_sub_f32_e32 v64, v64, v190
	v_add_f32_e32 v81, v95, v80
	v_exp_f32_e32 v80, v64
	v_sub_f32_e32 v65, v65, v190
	v_add_f32_e32 v64, v80, v81
	v_exp_f32_e32 v81, v65
	v_sub_f32_e32 v65, v66, v190
	v_exp_f32_e32 v82, v65
	v_sub_f32_e32 v65, v67, v190
	v_exp_f32_e32 v83, v65
	v_sub_f32_e32 v65, v68, v190
	v_exp_f32_e32 v84, v65
	v_sub_f32_e32 v65, v69, v190
	v_add_f32_e32 v64, v81, v64
	v_exp_f32_e32 v85, v65
	v_sub_f32_e32 v65, v70, v190
	v_add_f32_e32 v64, v82, v64
	v_exp_f32_e32 v86, v65
	v_sub_f32_e32 v65, v71, v190
	v_add_f32_e32 v64, v83, v64
	v_exp_f32_e32 v87, v65
	v_sub_f32_e32 v65, v72, v190
	v_add_f32_e32 v64, v84, v64
	v_exp_f32_e32 v69, v65
	v_sub_f32_e32 v65, v73, v190
	v_add_f32_e32 v64, v85, v64
	v_exp_f32_e32 v70, v65
	v_sub_f32_e32 v65, v74, v190
	v_add_f32_e32 v64, v86, v64
	v_exp_f32_e32 v71, v65
	v_sub_f32_e32 v65, v75, v190
	v_add_f32_e32 v64, v87, v64
	v_exp_f32_e32 v72, v65
	v_sub_f32_e32 v65, v76, v190
	v_add_f32_e32 v64, v69, v64
	v_exp_f32_e32 v73, v65
	v_sub_f32_e32 v65, v77, v190
	v_add_f32_e32 v64, v70, v64
	v_exp_f32_e32 v74, v65
	v_sub_f32_e32 v65, v78, v190
	v_add_f32_e32 v64, v71, v64
	v_exp_f32_e32 v75, v65
	v_sub_f32_e32 v65, v79, v190
	v_add_f32_e32 v64, v72, v64
	v_exp_f32_e32 v76, v65
	v_add_f32_e32 v64, v73, v64
	v_add_f32_e32 v64, v74, v64
	v_add3_u32 v77, s8, v182, v188
	v_add_f32_e32 v64, v75, v64
	v_add_u32_e32 v78, 0x4000, v77
	v_add_f32_e32 v68, v76, v64
	v_cvt_pk_bf16_f32 v64, v192, v193
	v_cvt_pk_bf16_f32 v65, v194, v195
	v_cvt_pk_bf16_f32 v66, v196, v197
	v_cvt_pk_bf16_f32 v67, v198, v199
	v_fmac_f32_e32 v68, v191, v174
	v_add_u32_e32 v174, 0x5000, v77
	v_add_u32_e32 v79, 0x6000, v77
	v_add_u32_e32 v77, 0x7000, v77
	v_mov_b32_e32 v191, v68
	ds_read2_b64 v[192:195], v78 offset0:136 offset1:138
	ds_read2_b64 v[196:199], v174 offset0:168 offset1:170
	ds_read2_b64 v[248:251], v79 offset0:200 offset1:202
	s_waitcnt lgkmcnt(2)
	v_mfma_f32_32x32x16_bf16 v[48:63], v[192:195], v[64:67], v[48:63]
	ds_read2_b64 v[192:195], v77 offset0:232 offset1:234
	s_waitcnt lgkmcnt(2)
	v_mfma_f32_32x32x16_bf16 v[32:47], v[196:199], v[64:67], v[32:47]
	ds_read2_b64 v[196:199], v78 offset0:140 offset1:142
	s_waitcnt lgkmcnt(2)
	v_mfma_f32_32x32x16_bf16 v[16:31], v[248:251], v[64:67], v[16:31]
	ds_read2_b64 v[248:251], v174 offset0:172 offset1:174
	s_waitcnt lgkmcnt(2)
	v_mfma_f32_32x32x16_bf16 v[0:15], v[192:195], v[64:67], v[0:15]
	ds_read2_b64 v[192:195], v79 offset0:204 offset1:206
	v_cvt_pk_bf16_f32 v64, v88, v89
	v_cvt_pk_bf16_f32 v65, v90, v91
	v_cvt_pk_bf16_f32 v66, v92, v93
	v_cvt_pk_bf16_f32 v67, v94, v95
	s_waitcnt lgkmcnt(2)
	s_nop 0
	v_mfma_f32_32x32x16_bf16 v[48:63], v[196:199], v[64:67], v[48:63]
	ds_read2_b64 v[196:199], v77 offset0:236 offset1:238
	s_waitcnt lgkmcnt(2)
	v_mfma_f32_32x32x16_bf16 v[32:47], v[248:251], v[64:67], v[32:47]
	ds_read2_b64 v[248:251], v78 offset0:144 offset1:146
	s_waitcnt lgkmcnt(2)
	v_mfma_f32_32x32x16_bf16 v[16:31], v[192:195], v[64:67], v[16:31]
	ds_read2_b64 v[192:195], v174 offset0:176 offset1:178
	s_waitcnt lgkmcnt(2)
	v_mfma_f32_32x32x16_bf16 v[0:15], v[196:199], v[64:67], v[0:15]
	ds_read2_b64 v[196:199], v79 offset0:208 offset1:210
	v_cvt_pk_bf16_f32 v64, v80, v81
	v_cvt_pk_bf16_f32 v65, v82, v83
	v_cvt_pk_bf16_f32 v66, v84, v85
	v_cvt_pk_bf16_f32 v67, v86, v87
	s_waitcnt lgkmcnt(2)
	s_nop 0
	v_mfma_f32_32x32x16_bf16 v[48:63], v[248:251], v[64:67], v[48:63]
	ds_read2_b64 v[248:251], v77 offset0:240 offset1:242
	s_waitcnt lgkmcnt(2)
	v_mfma_f32_32x32x16_bf16 v[32:47], v[192:195], v[64:67], v[32:47]
	ds_read2_b64 v[192:195], v78 offset0:148 offset1:150
	s_waitcnt lgkmcnt(2)
	v_mfma_f32_32x32x16_bf16 v[16:31], v[196:199], v[64:67], v[16:31]
	ds_read2_b64 v[196:199], v174 offset0:180 offset1:182
	s_waitcnt lgkmcnt(2)
	v_mfma_f32_32x32x16_bf16 v[0:15], v[248:251], v[64:67], v[0:15]
	ds_read2_b64 v[248:251], v79 offset0:212 offset1:214
	v_cvt_pk_bf16_f32 v64, v69, v70
	v_cvt_pk_bf16_f32 v65, v71, v72
	v_cvt_pk_bf16_f32 v66, v73, v74
	v_cvt_pk_bf16_f32 v67, v75, v76
	s_waitcnt lgkmcnt(2)
	s_nop 0
	v_mfma_f32_32x32x16_bf16 v[48:63], v[192:195], v[64:67], v[48:63]
	ds_read2_b64 v[192:195], v77 offset0:244 offset1:246
	s_waitcnt lgkmcnt(2)
	v_mfma_f32_32x32x16_bf16 v[32:47], v[196:199], v[64:67], v[32:47]
	s_waitcnt lgkmcnt(1)
	v_mfma_f32_32x32x16_bf16 v[16:31], v[248:251], v[64:67], v[16:31]
	s_waitcnt lgkmcnt(0)
	v_mov_b32_e32 v174, v190
	v_mfma_f32_32x32x16_bf16 v[0:15], v[192:195], v[64:67], v[0:15]
